# M1 row-major layout v2: rstd redistribution with 8 bpermutes + DPP quad broadcast (was 32 bpermutes)
# baseline (speedup 1.0000x reference)
.LBB0_958:
	v_bfe_u32 v192, v0, 4, 2
	v_and_b32_e32 v193, 3, v0
	v_lshl_or_b32 v194, v192, 2, v193
	v_lshlrev_b32_e32 v194, 2, v194
	ds_bpermute_b32 v176, v194, v140
	ds_bpermute_b32 v177, v194, v144
	ds_bpermute_b32 v178, v194, v148
	ds_bpermute_b32 v179, v194, v150
	ds_bpermute_b32 v180, v194, v136
	ds_bpermute_b32 v181, v194, v137
	ds_bpermute_b32 v182, v194, v152
	ds_bpermute_b32 v183, v194, v154
	v_lshlrev_b32_e32 v193, 2, v192
	v_and_b32_e32 v175, -16, v146
	v_add_u32_e32 v175, v175, v193
	v_lshlrev_b32_e32 v175, 13, v175
	v_and_b32_e32 v193, 15, v0
	v_lshlrev_b32_e32 v193, 3, v193
	v_lshrrev_b32_e32 v192, 5, v226
	v_lshl_or_b32 v193, v192, 6, v193
	v_lshl_or_b32 v193, s59, 9, v193
	v_or_b32_e32 v175, v175, v193
	s_waitcnt lgkmcnt(7)
	v_mov_b32_dpp v184, v176 quad_perm:[0,0,0,0] row_mask:0xf bank_mask:0xf
	v_mov_b32_dpp v185, v176 quad_perm:[1,1,1,1] row_mask:0xf bank_mask:0xf
	v_mov_b32_dpp v186, v176 quad_perm:[2,2,2,2] row_mask:0xf bank_mask:0xf
	v_mov_b32_dpp v187, v176 quad_perm:[3,3,3,3] row_mask:0xf bank_mask:0xf
	v_pk_mul_f32 v[126:127], v[126:127], v[184:185]
	v_pk_mul_f32 v[128:129], v[128:129], v[186:187]
	v_pk_mul_f32 v[130:131], v[130:131], v[184:185]
	v_pk_mul_f32 v[132:133], v[132:133], v[186:187]
	v_pk_mul_f32 v[118:119], v[118:119], v[184:185]
	v_pk_mul_f32 v[120:121], v[120:121], v[186:187]
	v_pk_mul_f32 v[122:123], v[122:123], v[184:185]
	v_pk_mul_f32 v[124:125], v[124:125], v[186:187]
	v_max_f32_e32 v118, 0, v118
	v_max_f32_e32 v119, 0, v119
	v_max_f32_e32 v120, 0, v120
	v_max_f32_e32 v121, 0, v121
	v_max_f32_e32 v122, 0, v122
	v_max_f32_e32 v123, 0, v123
	v_max_f32_e32 v124, 0, v124
	v_max_f32_e32 v125, 0, v125
	v_max_f32_e32 v126, 0, v126
	v_max_f32_e32 v127, 0, v127
	v_max_f32_e32 v128, 0, v128
	v_max_f32_e32 v129, 0, v129
	v_max_f32_e32 v130, 0, v130
	v_max_f32_e32 v131, 0, v131
	v_max_f32_e32 v132, 0, v132
	v_max_f32_e32 v133, 0, v133
	v_pk_mul_f32 v[118:119], v[118:119], v[118:119]
	v_pk_mul_f32 v[120:121], v[120:121], v[120:121]
	v_pk_mul_f32 v[122:123], v[122:123], v[122:123]
	v_pk_mul_f32 v[124:125], v[124:125], v[124:125]
	v_pk_mul_f32 v[126:127], v[126:127], v[126:127]
	v_pk_mul_f32 v[128:129], v[128:129], v[128:129]
	v_pk_mul_f32 v[130:131], v[130:131], v[130:131]
	v_pk_mul_f32 v[132:133], v[132:133], v[132:133]
	v_cvt_pk_bf16_f32 v188, v130, v126
	v_cvt_pk_bf16_f32 v189, v122, v118
	global_store_dwordx2 v175, v[188:189], s[4:5] sc1
	v_cvt_pk_bf16_f32 v190, v131, v127
	v_cvt_pk_bf16_f32 v191, v123, v119
	v_add_u32_e32 v192, 0x2000, v175
	global_store_dwordx2 v192, v[190:191], s[4:5] sc1
	v_cvt_pk_bf16_f32 v194, v132, v128
	v_cvt_pk_bf16_f32 v195, v124, v120
	v_add_u32_e32 v193, 0x4000, v175
	global_store_dwordx2 v193, v[194:195], s[4:5] sc1
	v_cvt_pk_bf16_f32 v196, v133, v129
	v_cvt_pk_bf16_f32 v197, v125, v121
	v_add_u32_e32 v2, 0x6000, v175
	global_store_dwordx2 v2, v[196:197], s[4:5] sc1
	s_waitcnt lgkmcnt(6)
	v_mov_b32_dpp v184, v177 quad_perm:[0,0,0,0] row_mask:0xf bank_mask:0xf
	v_mov_b32_dpp v185, v177 quad_perm:[1,1,1,1] row_mask:0xf bank_mask:0xf
	v_mov_b32_dpp v186, v177 quad_perm:[2,2,2,2] row_mask:0xf bank_mask:0xf
	v_mov_b32_dpp v187, v177 quad_perm:[3,3,3,3] row_mask:0xf bank_mask:0xf
	v_pk_mul_f32 v[110:111], v[110:111], v[184:185]
	v_pk_mul_f32 v[112:113], v[112:113], v[186:187]
	v_pk_mul_f32 v[114:115], v[114:115], v[184:185]
	v_pk_mul_f32 v[116:117], v[116:117], v[186:187]
	v_pk_mul_f32 v[102:103], v[102:103], v[184:185]
	v_pk_mul_f32 v[104:105], v[104:105], v[186:187]
	v_pk_mul_f32 v[106:107], v[106:107], v[184:185]
	v_pk_mul_f32 v[108:109], v[108:109], v[186:187]
	v_max_f32_e32 v102, 0, v102
	v_max_f32_e32 v103, 0, v103
	v_max_f32_e32 v104, 0, v104
	v_max_f32_e32 v105, 0, v105
	v_max_f32_e32 v106, 0, v106
	v_max_f32_e32 v107, 0, v107
	v_max_f32_e32 v108, 0, v108
	v_max_f32_e32 v109, 0, v109
	v_max_f32_e32 v110, 0, v110
	v_max_f32_e32 v111, 0, v111
	v_max_f32_e32 v112, 0, v112
	v_max_f32_e32 v113, 0, v113
	v_max_f32_e32 v114, 0, v114
	v_max_f32_e32 v115, 0, v115
	v_max_f32_e32 v116, 0, v116
	v_max_f32_e32 v117, 0, v117
	v_pk_mul_f32 v[102:103], v[102:103], v[102:103]
	v_pk_mul_f32 v[104:105], v[104:105], v[104:105]
	v_pk_mul_f32 v[106:107], v[106:107], v[106:107]
	v_pk_mul_f32 v[108:109], v[108:109], v[108:109]
	v_pk_mul_f32 v[110:111], v[110:111], v[110:111]
	v_pk_mul_f32 v[112:113], v[112:113], v[112:113]
	v_pk_mul_f32 v[114:115], v[114:115], v[114:115]
	v_pk_mul_f32 v[116:117], v[116:117], v[116:117]
	v_cvt_pk_bf16_f32 v188, v114, v110
	v_cvt_pk_bf16_f32 v189, v106, v102
	v_add_u32_e32 v3, 0x20000, v175
	global_store_dwordx2 v3, v[188:189], s[4:5] sc1
	v_cvt_pk_bf16_f32 v190, v115, v111
	v_cvt_pk_bf16_f32 v191, v107, v103
	v_add_u32_e32 v192, 0x22000, v175
	global_store_dwordx2 v192, v[190:191], s[4:5] sc1
	v_cvt_pk_bf16_f32 v194, v116, v112
	v_cvt_pk_bf16_f32 v195, v108, v104
	v_add_u32_e32 v193, 0x24000, v175
	global_store_dwordx2 v193, v[194:195], s[4:5] sc1
	v_cvt_pk_bf16_f32 v196, v117, v113
	v_cvt_pk_bf16_f32 v197, v109, v105
	v_add_u32_e32 v2, 0x26000, v175
	global_store_dwordx2 v2, v[196:197], s[4:5] sc1
	s_waitcnt lgkmcnt(5)
	v_mov_b32_dpp v184, v178 quad_perm:[0,0,0,0] row_mask:0xf bank_mask:0xf
	v_mov_b32_dpp v185, v178 quad_perm:[1,1,1,1] row_mask:0xf bank_mask:0xf
	v_mov_b32_dpp v186, v178 quad_perm:[2,2,2,2] row_mask:0xf bank_mask:0xf
	v_mov_b32_dpp v187, v178 quad_perm:[3,3,3,3] row_mask:0xf bank_mask:0xf
	v_pk_mul_f32 v[94:95], v[94:95], v[184:185]
	v_pk_mul_f32 v[96:97], v[96:97], v[186:187]
	v_pk_mul_f32 v[98:99], v[98:99], v[184:185]
	v_pk_mul_f32 v[100:101], v[100:101], v[186:187]
	v_pk_mul_f32 v[86:87], v[86:87], v[184:185]
	v_pk_mul_f32 v[88:89], v[88:89], v[186:187]
	v_pk_mul_f32 v[90:91], v[90:91], v[184:185]
	v_pk_mul_f32 v[92:93], v[92:93], v[186:187]
	v_max_f32_e32 v86, 0, v86
	v_max_f32_e32 v87, 0, v87
	v_max_f32_e32 v88, 0, v88
	v_max_f32_e32 v89, 0, v89
	v_max_f32_e32 v90, 0, v90
	v_max_f32_e32 v91, 0, v91
	v_max_f32_e32 v92, 0, v92
	v_max_f32_e32 v93, 0, v93
	v_max_f32_e32 v94, 0, v94
	v_max_f32_e32 v95, 0, v95
	v_max_f32_e32 v96, 0, v96
	v_max_f32_e32 v97, 0, v97
	v_max_f32_e32 v98, 0, v98
	v_max_f32_e32 v99, 0, v99
	v_max_f32_e32 v100, 0, v100
	v_max_f32_e32 v101, 0, v101
	v_pk_mul_f32 v[86:87], v[86:87], v[86:87]
	v_pk_mul_f32 v[88:89], v[88:89], v[88:89]
	v_pk_mul_f32 v[90:91], v[90:91], v[90:91]
	v_pk_mul_f32 v[92:93], v[92:93], v[92:93]
	v_pk_mul_f32 v[94:95], v[94:95], v[94:95]
	v_pk_mul_f32 v[96:97], v[96:97], v[96:97]
	v_pk_mul_f32 v[98:99], v[98:99], v[98:99]
	v_pk_mul_f32 v[100:101], v[100:101], v[100:101]
	v_cvt_pk_bf16_f32 v188, v98, v94
	v_cvt_pk_bf16_f32 v189, v90, v86
	v_add_u32_e32 v3, 0x40000, v175
	global_store_dwordx2 v3, v[188:189], s[4:5] sc1
	v_cvt_pk_bf16_f32 v190, v99, v95
	v_cvt_pk_bf16_f32 v191, v91, v87
	v_add_u32_e32 v192, 0x42000, v175
	global_store_dwordx2 v192, v[190:191], s[4:5] sc1
	v_cvt_pk_bf16_f32 v194, v100, v96
	v_cvt_pk_bf16_f32 v195, v92, v88
	v_add_u32_e32 v193, 0x44000, v175
	global_store_dwordx2 v193, v[194:195], s[4:5] sc1
	v_cvt_pk_bf16_f32 v196, v101, v97
	v_cvt_pk_bf16_f32 v197, v93, v89
	v_add_u32_e32 v2, 0x46000, v175
	global_store_dwordx2 v2, v[196:197], s[4:5] sc1
	s_waitcnt lgkmcnt(4)
	v_mov_b32_dpp v184, v179 quad_perm:[0,0,0,0] row_mask:0xf bank_mask:0xf
	v_mov_b32_dpp v185, v179 quad_perm:[1,1,1,1] row_mask:0xf bank_mask:0xf
	v_mov_b32_dpp v186, v179 quad_perm:[2,2,2,2] row_mask:0xf bank_mask:0xf
	v_mov_b32_dpp v187, v179 quad_perm:[3,3,3,3] row_mask:0xf bank_mask:0xf
	v_pk_mul_f32 v[78:79], v[78:79], v[184:185]
	v_pk_mul_f32 v[80:81], v[80:81], v[186:187]
	v_pk_mul_f32 v[82:83], v[82:83], v[184:185]
	v_pk_mul_f32 v[84:85], v[84:85], v[186:187]
	v_pk_mul_f32 v[70:71], v[70:71], v[184:185]
	v_pk_mul_f32 v[72:73], v[72:73], v[186:187]
	v_pk_mul_f32 v[74:75], v[74:75], v[184:185]
	v_pk_mul_f32 v[76:77], v[76:77], v[186:187]
	v_max_f32_e32 v70, 0, v70
	v_max_f32_e32 v71, 0, v71
	v_max_f32_e32 v72, 0, v72
	v_max_f32_e32 v73, 0, v73
	v_max_f32_e32 v74, 0, v74
	v_max_f32_e32 v75, 0, v75
	v_max_f32_e32 v76, 0, v76
	v_max_f32_e32 v77, 0, v77
	v_max_f32_e32 v78, 0, v78
	v_max_f32_e32 v79, 0, v79
	v_max_f32_e32 v80, 0, v80
	v_max_f32_e32 v81, 0, v81
	v_max_f32_e32 v82, 0, v82
	v_max_f32_e32 v83, 0, v83
	v_max_f32_e32 v84, 0, v84
	v_max_f32_e32 v85, 0, v85
	v_pk_mul_f32 v[70:71], v[70:71], v[70:71]
	v_pk_mul_f32 v[72:73], v[72:73], v[72:73]
	v_pk_mul_f32 v[74:75], v[74:75], v[74:75]
	v_pk_mul_f32 v[76:77], v[76:77], v[76:77]
	v_pk_mul_f32 v[78:79], v[78:79], v[78:79]
	v_pk_mul_f32 v[80:81], v[80:81], v[80:81]
	v_pk_mul_f32 v[82:83], v[82:83], v[82:83]
	v_pk_mul_f32 v[84:85], v[84:85], v[84:85]
	v_cvt_pk_bf16_f32 v188, v82, v78
	v_cvt_pk_bf16_f32 v189, v74, v70
	v_add_u32_e32 v3, 0x60000, v175
	global_store_dwordx2 v3, v[188:189], s[4:5] sc1
	v_cvt_pk_bf16_f32 v190, v83, v79
	v_cvt_pk_bf16_f32 v191, v75, v71
	v_add_u32_e32 v192, 0x62000, v175
	global_store_dwordx2 v192, v[190:191], s[4:5] sc1
	v_cvt_pk_bf16_f32 v194, v84, v80
	v_cvt_pk_bf16_f32 v195, v76, v72
	v_add_u32_e32 v193, 0x64000, v175
	global_store_dwordx2 v193, v[194:195], s[4:5] sc1
	v_cvt_pk_bf16_f32 v196, v85, v81
	v_cvt_pk_bf16_f32 v197, v77, v73
	v_add_u32_e32 v2, 0x66000, v175
	global_store_dwordx2 v2, v[196:197], s[4:5] sc1
	s_waitcnt lgkmcnt(3)
	v_mov_b32_dpp v184, v180 quad_perm:[0,0,0,0] row_mask:0xf bank_mask:0xf
	v_mov_b32_dpp v185, v180 quad_perm:[1,1,1,1] row_mask:0xf bank_mask:0xf
	v_mov_b32_dpp v186, v180 quad_perm:[2,2,2,2] row_mask:0xf bank_mask:0xf
	v_mov_b32_dpp v187, v180 quad_perm:[3,3,3,3] row_mask:0xf bank_mask:0xf
	v_pk_mul_f32 v[62:63], v[62:63], v[184:185]
	v_pk_mul_f32 v[64:65], v[64:65], v[186:187]
	v_pk_mul_f32 v[66:67], v[66:67], v[184:185]
	v_pk_mul_f32 v[68:69], v[68:69], v[186:187]
	v_pk_mul_f32 v[54:55], v[54:55], v[184:185]
	v_pk_mul_f32 v[56:57], v[56:57], v[186:187]
	v_pk_mul_f32 v[58:59], v[58:59], v[184:185]
	v_pk_mul_f32 v[60:61], v[60:61], v[186:187]
	v_max_f32_e32 v54, 0, v54
	v_max_f32_e32 v55, 0, v55
	v_max_f32_e32 v56, 0, v56
	v_max_f32_e32 v57, 0, v57
	v_max_f32_e32 v58, 0, v58
	v_max_f32_e32 v59, 0, v59
	v_max_f32_e32 v60, 0, v60
	v_max_f32_e32 v61, 0, v61
	v_max_f32_e32 v62, 0, v62
	v_max_f32_e32 v63, 0, v63
	v_max_f32_e32 v64, 0, v64
	v_max_f32_e32 v65, 0, v65
	v_max_f32_e32 v66, 0, v66
	v_max_f32_e32 v67, 0, v67
	v_max_f32_e32 v68, 0, v68
	v_max_f32_e32 v69, 0, v69
	v_pk_mul_f32 v[54:55], v[54:55], v[54:55]
	v_pk_mul_f32 v[56:57], v[56:57], v[56:57]
	v_pk_mul_f32 v[58:59], v[58:59], v[58:59]
	v_pk_mul_f32 v[60:61], v[60:61], v[60:61]
	v_pk_mul_f32 v[62:63], v[62:63], v[62:63]
	v_pk_mul_f32 v[64:65], v[64:65], v[64:65]
	v_pk_mul_f32 v[66:67], v[66:67], v[66:67]
	v_pk_mul_f32 v[68:69], v[68:69], v[68:69]
	v_cvt_pk_bf16_f32 v188, v66, v62
	v_cvt_pk_bf16_f32 v189, v58, v54
	v_add_u32_e32 v3, 0x100000, v175
	global_store_dwordx2 v3, v[188:189], s[4:5] sc1
	v_cvt_pk_bf16_f32 v190, v67, v63
	v_cvt_pk_bf16_f32 v191, v59, v55
	v_add_u32_e32 v192, 0x102000, v175
	global_store_dwordx2 v192, v[190:191], s[4:5] sc1
	v_cvt_pk_bf16_f32 v194, v68, v64
	v_cvt_pk_bf16_f32 v195, v60, v56
	v_add_u32_e32 v193, 0x104000, v175
	global_store_dwordx2 v193, v[194:195], s[4:5] sc1
	v_cvt_pk_bf16_f32 v196, v69, v65
	v_cvt_pk_bf16_f32 v197, v61, v57
	v_add_u32_e32 v2, 0x106000, v175
	global_store_dwordx2 v2, v[196:197], s[4:5] sc1
	s_waitcnt lgkmcnt(2)
	v_mov_b32_dpp v184, v181 quad_perm:[0,0,0,0] row_mask:0xf bank_mask:0xf
	v_mov_b32_dpp v185, v181 quad_perm:[1,1,1,1] row_mask:0xf bank_mask:0xf
	v_mov_b32_dpp v186, v181 quad_perm:[2,2,2,2] row_mask:0xf bank_mask:0xf
	v_mov_b32_dpp v187, v181 quad_perm:[3,3,3,3] row_mask:0xf bank_mask:0xf
	v_pk_mul_f32 v[46:47], v[46:47], v[184:185]
	v_pk_mul_f32 v[48:49], v[48:49], v[186:187]
	v_pk_mul_f32 v[50:51], v[50:51], v[184:185]
	v_pk_mul_f32 v[52:53], v[52:53], v[186:187]
	v_pk_mul_f32 v[38:39], v[38:39], v[184:185]
	v_pk_mul_f32 v[40:41], v[40:41], v[186:187]
	v_pk_mul_f32 v[42:43], v[42:43], v[184:185]
	v_pk_mul_f32 v[44:45], v[44:45], v[186:187]
	v_max_f32_e32 v38, 0, v38
	v_max_f32_e32 v39, 0, v39
	v_max_f32_e32 v40, 0, v40
	v_max_f32_e32 v41, 0, v41
	v_max_f32_e32 v42, 0, v42
	v_max_f32_e32 v43, 0, v43
	v_max_f32_e32 v44, 0, v44
	v_max_f32_e32 v45, 0, v45
	v_max_f32_e32 v46, 0, v46
	v_max_f32_e32 v47, 0, v47
	v_max_f32_e32 v48, 0, v48
	v_max_f32_e32 v49, 0, v49
	v_max_f32_e32 v50, 0, v50
	v_max_f32_e32 v51, 0, v51
	v_max_f32_e32 v52, 0, v52
	v_max_f32_e32 v53, 0, v53
	v_pk_mul_f32 v[38:39], v[38:39], v[38:39]
	v_pk_mul_f32 v[40:41], v[40:41], v[40:41]
	v_pk_mul_f32 v[42:43], v[42:43], v[42:43]
	v_pk_mul_f32 v[44:45], v[44:45], v[44:45]
	v_pk_mul_f32 v[46:47], v[46:47], v[46:47]
	v_pk_mul_f32 v[48:49], v[48:49], v[48:49]
	v_pk_mul_f32 v[50:51], v[50:51], v[50:51]
	v_pk_mul_f32 v[52:53], v[52:53], v[52:53]
	v_cvt_pk_bf16_f32 v188, v50, v46
	v_cvt_pk_bf16_f32 v189, v42, v38
	v_add_u32_e32 v3, 0x120000, v175
	global_store_dwordx2 v3, v[188:189], s[4:5] sc1
	v_cvt_pk_bf16_f32 v190, v51, v47
	v_cvt_pk_bf16_f32 v191, v43, v39
	v_add_u32_e32 v192, 0x122000, v175
	global_store_dwordx2 v192, v[190:191], s[4:5] sc1
	v_cvt_pk_bf16_f32 v194, v52, v48
	v_cvt_pk_bf16_f32 v195, v44, v40
	v_add_u32_e32 v193, 0x124000, v175
	global_store_dwordx2 v193, v[194:195], s[4:5] sc1
	v_cvt_pk_bf16_f32 v196, v53, v49
	v_cvt_pk_bf16_f32 v197, v45, v41
	v_add_u32_e32 v2, 0x126000, v175
	global_store_dwordx2 v2, v[196:197], s[4:5] sc1
	s_waitcnt lgkmcnt(1)
	v_mov_b32_dpp v184, v182 quad_perm:[0,0,0,0] row_mask:0xf bank_mask:0xf
	v_mov_b32_dpp v185, v182 quad_perm:[1,1,1,1] row_mask:0xf bank_mask:0xf
	v_mov_b32_dpp v186, v182 quad_perm:[2,2,2,2] row_mask:0xf bank_mask:0xf
	v_mov_b32_dpp v187, v182 quad_perm:[3,3,3,3] row_mask:0xf bank_mask:0xf
	v_pk_mul_f32 v[30:31], v[30:31], v[184:185]
	v_pk_mul_f32 v[32:33], v[32:33], v[186:187]
	v_pk_mul_f32 v[34:35], v[34:35], v[184:185]
	v_pk_mul_f32 v[36:37], v[36:37], v[186:187]
	v_pk_mul_f32 v[22:23], v[22:23], v[184:185]
	v_pk_mul_f32 v[24:25], v[24:25], v[186:187]
	v_pk_mul_f32 v[26:27], v[26:27], v[184:185]
	v_pk_mul_f32 v[28:29], v[28:29], v[186:187]
	v_max_f32_e32 v22, 0, v22
	v_max_f32_e32 v23, 0, v23
	v_max_f32_e32 v24, 0, v24
	v_max_f32_e32 v25, 0, v25
	v_max_f32_e32 v26, 0, v26
	v_max_f32_e32 v27, 0, v27
	v_max_f32_e32 v28, 0, v28
	v_max_f32_e32 v29, 0, v29
	v_max_f32_e32 v30, 0, v30
	v_max_f32_e32 v31, 0, v31
	v_max_f32_e32 v32, 0, v32
	v_max_f32_e32 v33, 0, v33
	v_max_f32_e32 v34, 0, v34
	v_max_f32_e32 v35, 0, v35
	v_max_f32_e32 v36, 0, v36
	v_max_f32_e32 v37, 0, v37
	v_pk_mul_f32 v[22:23], v[22:23], v[22:23]
	v_pk_mul_f32 v[24:25], v[24:25], v[24:25]
	v_pk_mul_f32 v[26:27], v[26:27], v[26:27]
	v_pk_mul_f32 v[28:29], v[28:29], v[28:29]
	v_pk_mul_f32 v[30:31], v[30:31], v[30:31]
	v_pk_mul_f32 v[32:33], v[32:33], v[32:33]
	v_pk_mul_f32 v[34:35], v[34:35], v[34:35]
	v_pk_mul_f32 v[36:37], v[36:37], v[36:37]
	v_cvt_pk_bf16_f32 v188, v34, v30
	v_cvt_pk_bf16_f32 v189, v26, v22
	v_add_u32_e32 v3, 0x140000, v175
	global_store_dwordx2 v3, v[188:189], s[4:5] sc1
	v_cvt_pk_bf16_f32 v190, v35, v31
	v_cvt_pk_bf16_f32 v191, v27, v23
	v_add_u32_e32 v192, 0x142000, v175
	global_store_dwordx2 v192, v[190:191], s[4:5] sc1
	v_cvt_pk_bf16_f32 v194, v36, v32
	v_cvt_pk_bf16_f32 v195, v28, v24
	v_add_u32_e32 v193, 0x144000, v175
	global_store_dwordx2 v193, v[194:195], s[4:5] sc1
	v_cvt_pk_bf16_f32 v196, v37, v33
	v_cvt_pk_bf16_f32 v197, v29, v25
	v_add_u32_e32 v2, 0x146000, v175
	global_store_dwordx2 v2, v[196:197], s[4:5] sc1
	s_waitcnt lgkmcnt(0)
	v_mov_b32_dpp v184, v183 quad_perm:[0,0,0,0] row_mask:0xf bank_mask:0xf
	v_mov_b32_dpp v185, v183 quad_perm:[1,1,1,1] row_mask:0xf bank_mask:0xf
	v_mov_b32_dpp v186, v183 quad_perm:[2,2,2,2] row_mask:0xf bank_mask:0xf
	v_mov_b32_dpp v187, v183 quad_perm:[3,3,3,3] row_mask:0xf bank_mask:0xf
	v_pk_mul_f32 v[14:15], v[14:15], v[184:185]
	v_pk_mul_f32 v[16:17], v[16:17], v[186:187]
	v_pk_mul_f32 v[18:19], v[18:19], v[184:185]
	v_pk_mul_f32 v[20:21], v[20:21], v[186:187]
	v_pk_mul_f32 v[6:7], v[6:7], v[184:185]
	v_pk_mul_f32 v[8:9], v[8:9], v[186:187]
	v_pk_mul_f32 v[10:11], v[10:11], v[184:185]
	v_pk_mul_f32 v[12:13], v[12:13], v[186:187]
	v_max_f32_e32 v6, 0, v6
	v_max_f32_e32 v7, 0, v7
	v_max_f32_e32 v8, 0, v8
	v_max_f32_e32 v9, 0, v9
	v_max_f32_e32 v10, 0, v10
	v_max_f32_e32 v11, 0, v11
	v_max_f32_e32 v12, 0, v12
	v_max_f32_e32 v13, 0, v13
	v_max_f32_e32 v14, 0, v14
	v_max_f32_e32 v15, 0, v15
	v_max_f32_e32 v16, 0, v16
	v_max_f32_e32 v17, 0, v17
	v_max_f32_e32 v18, 0, v18
	v_max_f32_e32 v19, 0, v19
	v_max_f32_e32 v20, 0, v20
	v_max_f32_e32 v21, 0, v21
	v_pk_mul_f32 v[6:7], v[6:7], v[6:7]
	v_pk_mul_f32 v[8:9], v[8:9], v[8:9]
	v_pk_mul_f32 v[10:11], v[10:11], v[10:11]
	v_pk_mul_f32 v[12:13], v[12:13], v[12:13]
	v_pk_mul_f32 v[14:15], v[14:15], v[14:15]
	v_pk_mul_f32 v[16:17], v[16:17], v[16:17]
	v_pk_mul_f32 v[18:19], v[18:19], v[18:19]
	v_pk_mul_f32 v[20:21], v[20:21], v[20:21]
	v_cvt_pk_bf16_f32 v188, v18, v14
	v_cvt_pk_bf16_f32 v189, v10, v6
	v_add_u32_e32 v3, 0x160000, v175
	global_store_dwordx2 v3, v[188:189], s[4:5] sc1
	v_cvt_pk_bf16_f32 v190, v19, v15
	v_cvt_pk_bf16_f32 v191, v11, v7
	v_add_u32_e32 v192, 0x162000, v175
	global_store_dwordx2 v192, v[190:191], s[4:5] sc1
	v_cvt_pk_bf16_f32 v194, v20, v16
	v_cvt_pk_bf16_f32 v195, v12, v8
	v_add_u32_e32 v193, 0x164000, v175
	global_store_dwordx2 v193, v[194:195], s[4:5] sc1
	v_cvt_pk_bf16_f32 v196, v21, v17
	v_cvt_pk_bf16_f32 v197, v13, v9
	v_add_u32_e32 v2, 0x166000, v175
	global_store_dwordx2 v2, v[196:197], s[4:5] sc1
	s_andn2_b64 vcc, exec, s[20:21]
	s_mov_b64 s[20:21], -1
	s_cbranch_vccnz .LBB0_936
	s_andn2_b64 vcc, exec, s[2:3]
	s_cbranch_vccnz .LBB0_935
	s_barrier
	s_branch .LBB0_935
